# v026: v025c + dead address materialisation (123 v_readlane/v_mov per item) removed from the conv_item_p LayerNorm phase
# speedup vs baseline: 1.0029x; 1.0029x over previous
.LBB0_433:
	s_or_b64 exec, exec, s[14:15]
	v_lshlrev_b32_e32 v81, 16, v81
	v_lshlrev_b32_e32 v122, 16, v54
	v_mul_f32_e32 v54, v165, v81
	v_fmac_f32_e32 v54, v163, v122
	s_waitcnt lgkmcnt(1)
	v_lshlrev_b32_e32 v121, 16, v121
	v_fmac_f32_e32 v54, v164, v121
	v_lshlrev_b32_e32 v105, 16, v105
	v_mul_f32_e32 v54, v54, v105
	v_lshlrev_b32_e32 v105, 16, v76
	v_mul_f32_e32 v76, v165, v122
	v_fmac_f32_e32 v76, v163, v105
	v_fmac_f32_e32 v76, v164, v81
	v_lshlrev_b32_e32 v81, 16, v120
	v_mul_f32_e32 v76, v76, v81
	v_lshlrev_b32_e32 v81, 16, v80
	v_mul_f32_e32 v80, v165, v105
	v_fmac_f32_e32 v80, v163, v81
	v_fmac_f32_e32 v80, v164, v122
	v_lshlrev_b32_e32 v119, 16, v119
	v_mul_f32_e32 v80, v80, v119
	v_lshlrev_b32_e32 v119, 16, v79
	v_mul_f32_e32 v79, v165, v81
	v_fmac_f32_e32 v79, v163, v119
	v_fmac_f32_e32 v79, v164, v105
	v_lshlrev_b32_e32 v105, 16, v118
	v_mul_f32_e32 v79, v79, v105
	v_lshlrev_b32_e32 v105, 16, v78
	v_mul_f32_e32 v78, v165, v119
	v_fmac_f32_e32 v78, v163, v105
	v_fmac_f32_e32 v78, v164, v81
	v_lshlrev_b32_e32 v81, 16, v117
	v_mul_f32_e32 v78, v78, v81
	v_lshlrev_b32_e32 v81, 16, v77
	v_mul_f32_e32 v77, v165, v105
	v_fmac_f32_e32 v77, v163, v81
	v_fmac_f32_e32 v77, v164, v119
	v_lshlrev_b32_e32 v116, 16, v116
	v_mul_f32_e32 v77, v77, v116
	v_lshlrev_b32_e32 v116, 16, v59
	v_mul_f32_e32 v59, v165, v81
	v_fmac_f32_e32 v59, v163, v116
	v_fmac_f32_e32 v59, v164, v105
	v_lshlrev_b32_e32 v105, 16, v115
	v_mul_f32_e32 v59, v59, v105
	v_lshlrev_b32_e32 v105, 16, v58
	v_mul_f32_e32 v58, v165, v116
	v_fmac_f32_e32 v58, v163, v105
	v_fmac_f32_e32 v58, v164, v81
	v_lshlrev_b32_e32 v81, 16, v114
	v_mul_f32_e32 v58, v58, v81
	v_lshlrev_b32_e32 v81, 16, v57
	v_mul_f32_e32 v57, v165, v105
	v_fmac_f32_e32 v57, v163, v81
	v_fmac_f32_e32 v57, v164, v116
	v_lshlrev_b32_e32 v113, 16, v113
	v_mul_f32_e32 v57, v57, v113
	v_lshlrev_b32_e32 v113, 16, v56
	v_mul_f32_e32 v56, v165, v81
	v_fmac_f32_e32 v56, v163, v113
	v_fmac_f32_e32 v56, v164, v105
	v_lshlrev_b32_e32 v105, 16, v112
	v_mul_f32_e32 v56, v56, v105
	v_lshlrev_b32_e32 v105, 16, v55
	v_mul_f32_e32 v55, v165, v113
	v_fmac_f32_e32 v55, v163, v105
	v_fmac_f32_e32 v55, v164, v81
	v_lshlrev_b32_e32 v81, 16, v111
	v_mul_f32_e32 v55, v55, v81
	v_lshlrev_b32_e32 v81, 16, v53
	v_mul_f32_e32 v53, v165, v105
	v_fmac_f32_e32 v53, v163, v81
	v_fmac_f32_e32 v53, v164, v113
	v_lshlrev_b32_e32 v110, 16, v110
	v_mul_f32_e32 v53, v53, v110
	v_lshlrev_b32_e32 v52, 16, v52
	v_mul_f32_e32 v110, v165, v81
	v_fmac_f32_e32 v110, v163, v52
	v_fmac_f32_e32 v110, v164, v105
	v_lshlrev_b32_e32 v105, 16, v109
	v_mul_f32_e32 v120, v110, v105
	v_lshlrev_b32_e32 v51, 16, v51
	v_mul_f32_e32 v105, v165, v52
	v_fmac_f32_e32 v105, v163, v51
	v_fmac_f32_e32 v105, v164, v81
	v_lshlrev_b32_e32 v81, 16, v108
	v_mul_f32_e32 v81, v105, v81
	v_lshlrev_b32_e32 v50, 16, v50
	v_mul_f32_e32 v105, v165, v51
	v_fmac_f32_e32 v105, v163, v50
	v_lshlrev_b32_e32 v104, 16, v104
	v_mul_f32_e32 v50, v165, v50
	v_fmac_f32_e32 v50, v163, v104
	v_fmac_f32_e32 v50, v164, v51
	v_lshlrev_b32_e32 v51, 16, v106
	v_readlane_b32 s15, v251, 9
	v_fmac_f32_e32 v105, v164, v52
	v_lshlrev_b32_e32 v52, 16, v107
	v_mul_f32_e32 v50, v50, v51
	v_mov_b32_e32 v51, s15
	s_add_i32 s30, 0, 0x22010
	v_mul_f32_e32 v52, v105, v52
	s_waitcnt lgkmcnt(0)
	s_barrier
	v_and_b32_e32 v104, 30, v64
	v_and_b32_e32 v105, 1, v64
	v_lshlrev_b32_e32 v104, 5, v104
	v_lshl_add_u32 v104, v105, 2, v104
	v_add_u32_e32 v104, 0x22000, v104
	ds_read2_b32 v[106:107], v104 offset1:2
	ds_read2_b32 v[108:109], v104 offset0:4 offset1:6
	ds_read2_b32 v[110:111], v104 offset0:8 offset1:10
	ds_read2_b32 v[112:113], v104 offset0:12 offset1:14
	v_cmp_eq_u32_e32 vcc, 1, v105
	s_mov_b32 s20, 0x3b000000
	s_waitcnt lgkmcnt(0)
	v_add_f32_e32 v106, v106, v107
	v_add_f32_e32 v108, v108, v109
	v_add_f32_e32 v106, v106, v108
	v_add_f32_e32 v110, v110, v111
	v_add_f32_e32 v106, v106, v110
	v_add_f32_e32 v112, v112, v113
	v_add_f32_e32 v106, v106, v112
	s_nop 1
	v_mov_b32_dpp v107, v106 quad_perm:[1,0,3,2] row_mask:0xf bank_mask:0xf
	v_cndmask_b32_e32 v212, v106, v107, vcc
	v_cndmask_b32_e32 v108, v107, v106, vcc
	v_mul_f32_e32 v109, 0x3b000000, v212
	v_mul_f32_e32 v109, v109, v109
	v_fma_f32 v108, v108, s20, -v109
	v_max_f32_e32 v108, 0, v108
	v_add_f32_e32 v108, 0x358637bd, v108
	v_rsq_f32_e32 v213, v108
	s_nop 1
	v_readlane_b32 s20, v212, 0
	v_readlane_b32 s21, v213, 0
	s_nop 1
	s_add_i32 s29, 0, 0x22020
	s_add_i32 s28, 0, 0x22030
	v_mov_b32_e32 v51, s20
	s_mov_b32 s16, 0x3b000000
	v_mov_b32_e32 v104, s21
	v_fmac_f32_e32 v49, 0xbb000000, v51
	v_cvt_pk_bf16_f32 v14, v14, s0
	ds_write_b16 v86, v14
	v_mul_f32_e32 v49, v49, v104
	v_fma_f32 v49, v143, v49, v142
	v_cvt_pk_bf16_f32 v14, v50, s0
	ds_write_b16 v86, v14 offset:16384
	v_mul_f32_e32 v14, 0xbfb8aa3b, v49
	v_exp_f32_e32 v14, v14
	v_cvt_pk_bf16_f32 v15, v15, s0
	v_cvt_pk_bf16_f32 v12, v12, s0
	v_add_f32_e32 v14, 1.0, v14
	v_rcp_f32_e32 v14, v14
	v_cvt_pk_bf16_f32 v13, v13, s0
	v_cvt_pk_bf16_f32 v4, v4, s0
	v_cvt_pk_bf16_f32 v5, v5, s0
	v_mul_f32_e32 v14, v49, v14
	v_cvt_pk_bf16_f32 v14, v14, s0
	ds_write_b16 v86, v14 offset:32768
	v_readlane_b32 s20, v212, 2
	v_readlane_b32 s21, v213, 2
	s_nop 1
	v_cvt_pk_bf16_f32 v0, v0, s0
	v_cvt_pk_bf16_f32 v1, v1, s0
	v_mov_b32_e32 v14, s20
	v_mov_b32_e32 v49, s21
	v_fmac_f32_e32 v47, 0xbb000000, v14
	ds_write_b16 v86, v15 offset:1024
	v_cvt_pk_bf16_f32 v15, v52, s0
	v_mul_f32_e32 v14, v47, v49
	v_fma_f32 v14, v143, v14, v142
	ds_write_b16 v86, v15 offset:17408
	v_mul_f32_e32 v15, 0xbfb8aa3b, v14
	v_exp_f32_e32 v15, v15
	s_or_b32 s14, s33, s45
	v_lshlrev_b32_e32 v192, 1, v28
	v_add_f32_e32 v15, 1.0, v15
	v_rcp_f32_e32 v15, v15
	v_mov_b32_e32 v49, v193
	v_mul_f32_e32 v14, v14, v15
	v_cvt_pk_bf16_f32 v14, v14, s0
	ds_write_b16 v86, v14 offset:33792
	v_readlane_b32 s20, v212, 4
	v_readlane_b32 s21, v213, 4
	s_nop 1
	s_nop 0
	v_mov_b32_e32 v14, s20
	v_mov_b32_e32 v15, s21
	v_fmac_f32_e32 v45, 0xbb000000, v14
	ds_write_b16 v86, v12 offset:2048
	v_cvt_pk_bf16_f32 v12, v81, s0
	v_mul_f32_e32 v14, v45, v15
	v_fma_f32 v14, v143, v14, v142
	ds_write_b16 v86, v12 offset:18432
	v_mul_f32_e32 v12, 0xbfb8aa3b, v14
	v_exp_f32_e32 v12, v12
	v_mov_b32_e32 v45, v193
	v_mov_b32_e32 v47, v193
	v_add_f32_e32 v12, 1.0, v12
	v_rcp_f32_e32 v12, v12
	s_nop 0
	v_mul_f32_e32 v12, v14, v12
	v_cvt_pk_bf16_f32 v12, v12, s0
	ds_write_b16 v86, v12 offset:34816
	v_readlane_b32 s20, v212, 6
	v_readlane_b32 s21, v213, 6
	s_nop 1
	s_nop 0
	v_mov_b32_e32 v12, s20
	v_mov_b32_e32 v14, s21
	v_fmac_f32_e32 v43, 0xbb000000, v12
	ds_write_b16 v86, v13 offset:3072
	v_cvt_pk_bf16_f32 v13, v120, s0
	v_mul_f32_e32 v12, v43, v14
	v_fma_f32 v12, v143, v12, v142
	ds_write_b16 v86, v13 offset:19456
	v_mul_f32_e32 v13, 0xbfb8aa3b, v12
	v_exp_f32_e32 v13, v13
	s_nop 0
	v_add_f32_e32 v13, 1.0, v13
	v_rcp_f32_e32 v13, v13
	s_nop 0
	v_mul_f32_e32 v12, v12, v13
	v_cvt_pk_bf16_f32 v12, v12, s0
	ds_write_b16 v86, v12 offset:35840
	v_readlane_b32 s20, v212, 8
	v_readlane_b32 s21, v213, 8
	s_nop 1
	s_nop 0
	v_mov_b32_e32 v12, s20
	v_mov_b32_e32 v13, s21
	v_fmac_f32_e32 v27, 0xbb000000, v12
	ds_write_b16 v86, v4 offset:4096
	v_cvt_pk_bf16_f32 v4, v53, s0
	v_mul_f32_e32 v12, v27, v13
	v_fma_f32 v12, v143, v12, v142
	ds_write_b16 v86, v4 offset:20480
	v_mul_f32_e32 v4, 0xbfb8aa3b, v12
	v_exp_f32_e32 v4, v4
	v_mov_b32_e32 v43, v193
	v_add_f32_e32 v4, 1.0, v4
	v_rcp_f32_e32 v4, v4
	s_nop 0
	v_mul_f32_e32 v4, v12, v4
	v_cvt_pk_bf16_f32 v4, v4, s0
	ds_write_b16 v86, v4 offset:36864
	v_readlane_b32 s20, v212, 10
	v_readlane_b32 s21, v213, 10
	s_nop 1
	s_nop 0
	s_nop 0
	s_nop 0
	v_mov_b32_e32 v4, s20
	v_mov_b32_e32 v12, s21
	v_fmac_f32_e32 v26, 0xbb000000, v4
	ds_write_b16 v86, v5 offset:5120
	v_cvt_pk_bf16_f32 v5, v55, s0
	v_mul_f32_e32 v4, v26, v12
	v_fma_f32 v4, v143, v4, v142
	ds_write_b16 v86, v5 offset:21504
	v_mul_f32_e32 v5, 0xbfb8aa3b, v4
	v_exp_f32_e32 v5, v5
	s_nop 0
	v_add_f32_e32 v5, 1.0, v5
	v_rcp_f32_e32 v5, v5
	s_nop 0
	v_mul_f32_e32 v4, v4, v5
	v_cvt_pk_bf16_f32 v4, v4, s0
	ds_write_b16 v86, v4 offset:37888
	v_readlane_b32 s20, v212, 12
	v_readlane_b32 s21, v213, 12
	s_nop 1
	s_nop 0
	s_nop 0
	v_mov_b32_e32 v4, s20
	v_mov_b32_e32 v5, s21
	v_fmac_f32_e32 v25, 0xbb000000, v4
	ds_write_b16 v86, v0 offset:6144
	v_cvt_pk_bf16_f32 v0, v56, s0
	v_mul_f32_e32 v4, v25, v5
	v_fma_f32 v4, v143, v4, v142
	ds_write_b16 v86, v0 offset:22528
	v_mul_f32_e32 v0, 0xbfb8aa3b, v4
	v_exp_f32_e32 v0, v0
	s_nop 0
	v_add_f32_e32 v0, 1.0, v0
	v_rcp_f32_e32 v0, v0
	s_nop 0
	v_mul_f32_e32 v0, v4, v0
	v_cvt_pk_bf16_f32 v0, v0, s0
	ds_write_b16 v86, v0 offset:38912
	v_readlane_b32 s20, v212, 14
	v_readlane_b32 s21, v213, 14
	s_nop 1
	s_nop 0
	v_mov_b32_e32 v0, s20
	v_mov_b32_e32 v4, s21
	v_fmac_f32_e32 v23, 0xbb000000, v0
	ds_write_b16 v86, v1 offset:7168
	v_cvt_pk_bf16_f32 v1, v57, s0
	v_mul_f32_e32 v0, v23, v4
	v_fma_f32 v0, v143, v0, v142
	ds_write_b16 v86, v1 offset:23552
	v_mul_f32_e32 v1, 0xbfb8aa3b, v0
	v_exp_f32_e32 v1, v1
	s_nop 0
	v_add_f32_e32 v1, 1.0, v1
	v_rcp_f32_e32 v1, v1
	s_nop 0
	v_mul_f32_e32 v0, v0, v1
	v_cvt_pk_bf16_f32 v0, v0, s0
	ds_write_b16 v86, v0 offset:39936
	v_readlane_b32 s20, v212, 16
	v_readlane_b32 s21, v213, 16
	s_nop 1
	s_nop 0
	v_mov_b32_e32 v0, s20
	v_mov_b32_e32 v1, s21
	v_fmac_f32_e32 v24, 0xbb000000, v0
	v_mul_f32_e32 v0, v24, v1
	v_cvt_pk_bf16_f32 v1, v10, s0
	v_fma_f32 v0, v143, v0, v142
	ds_write_b16 v86, v1 offset:8192
	v_cvt_pk_bf16_f32 v1, v58, s0
	ds_write_b16 v86, v1 offset:24576
	v_mul_f32_e32 v1, 0xbfb8aa3b, v0
	v_exp_f32_e32 v1, v1
	s_nop 0
	v_add_f32_e32 v1, 1.0, v1
	v_rcp_f32_e32 v1, v1
	s_nop 0
	v_mul_f32_e32 v0, v0, v1
	v_cvt_pk_bf16_f32 v0, v0, s0
	ds_write_b16 v86, v0 offset:40960
	v_readlane_b32 s20, v212, 18
	v_readlane_b32 s21, v213, 18
	s_nop 1
	s_nop 0
	v_mov_b32_e32 v0, s20
	v_mov_b32_e32 v1, s21
	v_fmac_f32_e32 v22, 0xbb000000, v0
	v_mul_f32_e32 v0, v22, v1
	v_cvt_pk_bf16_f32 v1, v11, s0
	v_fma_f32 v0, v143, v0, v142
	ds_write_b16 v86, v1 offset:9216
	v_cvt_pk_bf16_f32 v1, v59, s0
	ds_write_b16 v86, v1 offset:25600
	v_mul_f32_e32 v1, 0xbfb8aa3b, v0
	v_exp_f32_e32 v1, v1
	s_nop 0
	v_add_f32_e32 v1, 1.0, v1
	v_rcp_f32_e32 v1, v1
	s_nop 0
	v_mul_f32_e32 v0, v0, v1
	v_cvt_pk_bf16_f32 v0, v0, s0
	ds_write_b16 v86, v0 offset:41984
	v_readlane_b32 s20, v212, 20
	v_readlane_b32 s21, v213, 20
	s_nop 1
	s_nop 0
	v_mov_b32_e32 v0, s20
	v_mov_b32_e32 v1, s21
	v_fmac_f32_e32 v21, 0xbb000000, v0
	v_mul_f32_e32 v0, v21, v1
	v_cvt_pk_bf16_f32 v1, v8, s0
	v_fma_f32 v0, v143, v0, v142
	ds_write_b16 v86, v1 offset:10240
	v_cvt_pk_bf16_f32 v1, v77, s0
	ds_write_b16 v86, v1 offset:26624
	v_mul_f32_e32 v1, 0xbfb8aa3b, v0
	v_exp_f32_e32 v1, v1
	s_nop 0
	v_add_f32_e32 v1, 1.0, v1
	v_rcp_f32_e32 v1, v1
	s_nop 0
	v_mul_f32_e32 v0, v0, v1
	v_cvt_pk_bf16_f32 v0, v0, s0
	ds_write_b16 v86, v0 offset:43008
	v_readlane_b32 s20, v212, 22
	v_readlane_b32 s21, v213, 22
	s_nop 1
	s_nop 0
	v_mov_b32_e32 v0, s20
	v_mov_b32_e32 v1, s21
	v_fmac_f32_e32 v20, 0xbb000000, v0
	v_mul_f32_e32 v0, v20, v1
	v_cvt_pk_bf16_f32 v1, v9, s0
	v_fma_f32 v0, v143, v0, v142
	ds_write_b16 v86, v1 offset:11264
	v_cvt_pk_bf16_f32 v1, v78, s0
	ds_write_b16 v86, v1 offset:27648
	v_mul_f32_e32 v1, 0xbfb8aa3b, v0
	v_exp_f32_e32 v1, v1
	s_nop 0
	v_add_f32_e32 v1, 1.0, v1
	v_rcp_f32_e32 v1, v1
	s_nop 0
	v_mul_f32_e32 v0, v0, v1
	v_cvt_pk_bf16_f32 v0, v0, s0
	ds_write_b16 v86, v0 offset:44032
	v_readlane_b32 s20, v212, 24
	v_readlane_b32 s21, v213, 24
	s_nop 1
	s_nop 0
	v_mov_b32_e32 v0, s20
	v_mov_b32_e32 v1, s21
	v_fmac_f32_e32 v19, 0xbb000000, v0
	v_mul_f32_e32 v0, v19, v1
	v_cvt_pk_bf16_f32 v1, v2, s0
	v_fma_f32 v0, v143, v0, v142
	ds_write_b16 v86, v1 offset:12288
	v_cvt_pk_bf16_f32 v1, v79, s0
	ds_write_b16 v86, v1 offset:28672
	v_mul_f32_e32 v1, 0xbfb8aa3b, v0
	v_exp_f32_e32 v1, v1
	s_nop 0
	v_add_f32_e32 v1, 1.0, v1
	v_rcp_f32_e32 v1, v1
	s_nop 0
	v_mul_f32_e32 v0, v0, v1
	v_cvt_pk_bf16_f32 v0, v0, s0
	ds_write_b16 v86, v0 offset:45056
	v_readlane_b32 s20, v212, 26
	v_readlane_b32 s21, v213, 26
	s_nop 1
	s_nop 0
	v_mov_b32_e32 v0, s20
	v_mov_b32_e32 v1, s21
	v_fmac_f32_e32 v18, 0xbb000000, v0
	v_mul_f32_e32 v0, v18, v1
	v_cvt_pk_bf16_f32 v1, v3, s0
	v_fma_f32 v0, v143, v0, v142
	ds_write_b16 v86, v1 offset:13312
	v_cvt_pk_bf16_f32 v1, v80, s0
	ds_write_b16 v86, v1 offset:29696
	v_mul_f32_e32 v1, 0xbfb8aa3b, v0
	v_exp_f32_e32 v1, v1
	s_nop 0
	v_add_f32_e32 v1, 1.0, v1
	v_rcp_f32_e32 v1, v1
	s_nop 0
	v_mul_f32_e32 v0, v0, v1
	v_cvt_pk_bf16_f32 v0, v0, s0
	ds_write_b16 v86, v0 offset:46080
	v_readlane_b32 s20, v212, 28
	v_readlane_b32 s21, v213, 28
	s_nop 1
	s_nop 0
	v_mov_b32_e32 v0, s20
	v_mov_b32_e32 v1, s21
	v_fmac_f32_e32 v17, 0xbb000000, v0
	v_mul_f32_e32 v0, v17, v1
	v_cvt_pk_bf16_f32 v1, v6, s0
	v_fma_f32 v0, v143, v0, v142
	ds_write_b16 v86, v1 offset:14336
	v_cvt_pk_bf16_f32 v1, v76, s0
	ds_write_b16 v86, v1 offset:30720
	v_mul_f32_e32 v1, 0xbfb8aa3b, v0
	v_exp_f32_e32 v1, v1
	s_nop 0
	v_add_f32_e32 v1, 1.0, v1
	v_rcp_f32_e32 v1, v1
	s_nop 0
	v_mul_f32_e32 v0, v0, v1
	v_cvt_pk_bf16_f32 v0, v0, s0
	ds_write_b16 v86, v0 offset:47104
	v_readlane_b32 s20, v212, 30
	v_readlane_b32 s21, v213, 30
	s_nop 1
	s_nop 0
	v_mov_b32_e32 v0, s20
	v_mov_b32_e32 v1, s21
	v_fmac_f32_e32 v16, 0xbb000000, v0
	s_ashr_i32 s15, s14, 31
	s_mov_b64 s[16:17], s[42:43]
	v_mul_f32_e32 v0, v16, v1
	v_cvt_pk_bf16_f32 v1, v7, s0
	v_fma_f32 v0, v143, v0, v142
	ds_write_b16 v86, v1 offset:15360
	v_cvt_pk_bf16_f32 v1, v54, s0
	ds_write_b16 v86, v1 offset:31744
	v_mul_f32_e32 v1, 0xbfb8aa3b, v0
	v_exp_f32_e32 v1, v1
	s_lshl_b64 s[14:15], s[14:15], 12
	v_add_f32_e32 v1, 1.0, v1
	v_rcp_f32_e32 v1, v1
	s_nop 0
	v_mul_f32_e32 v0, v0, v1
	v_cvt_pk_bf16_f32 v0, v0, s0
	ds_write_b16 v86, v0 offset:48128
	s_waitcnt lgkmcnt(0)
	s_barrier
	s_add_u32 s14, s16, s14
	s_addc_u32 s15, s17, s15
	s_add_u32 s14, s14, 0x14000000
	ds_read_b128 v[0:3], v92
	s_addc_u32 s15, s15, 0
	v_lshl_add_u64 v[4:5], s[14:15], 0, v[42:43]
	v_lshl_add_u64 v[6:7], v[30:31], 1, v[4:5]
	v_lshl_add_u64 v[6:7], v[6:7], 0, v[192:193]
	s_waitcnt lgkmcnt(0)
	global_store_dwordx4 v[6:7], v[0:3], off
	ds_read_b128 v[0:3], v93
	v_lshl_add_u64 v[6:7], s[14:15], 0, v[44:45]
	v_lshl_add_u64 v[6:7], v[32:33], 1, v[6:7]
	v_lshl_add_u64 v[6:7], v[6:7], 0, v[192:193]
	s_add_i32 s54, s54, 1
	s_waitcnt lgkmcnt(0)
	global_store_dwordx4 v[6:7], v[0:3], off
	ds_read_b128 v[0:3], v94
	v_lshl_add_u64 v[6:7], v[34:35], 1, v[4:5]
	v_lshl_add_u64 v[6:7], v[6:7], 0, v[192:193]
	v_lshl_add_u64 v[4:5], v[38:39], 1, v[4:5]
	v_lshl_add_u64 v[4:5], v[4:5], 0, v[192:193]
	s_waitcnt lgkmcnt(0)
	global_store_dwordx4 v[6:7], v[0:3], off
	ds_read_b128 v[0:3], v95
	v_lshl_add_u64 v[6:7], s[14:15], 0, v[46:47]
	v_lshl_add_u64 v[6:7], v[36:37], 1, v[6:7]
	v_lshl_add_u64 v[6:7], v[6:7], 0, v[192:193]
	s_cmp_eq_u32 s54, 4
	s_waitcnt lgkmcnt(0)
	global_store_dwordx4 v[6:7], v[0:3], off
	ds_read_b128 v[0:3], v96
	s_waitcnt lgkmcnt(0)
	global_store_dwordx4 v[4:5], v[0:3], off
	ds_read_b128 v[0:3], v97
	v_lshl_add_u64 v[4:5], s[14:15], 0, v[48:49]
	v_lshl_add_u64 v[4:5], v[40:41], 1, v[4:5]
	v_lshl_add_u64 v[4:5], v[4:5], 0, v[192:193]
	s_waitcnt lgkmcnt(0)
	global_store_dwordx4 v[4:5], v[0:3], off
	s_waitcnt lgkmcnt(0)
	s_barrier
	s_cbranch_scc1 .LBB0_569
